# GEMM unit end: no wait for the epilogue stores to drain before the workgroup barrier; next unit's first two LDS-DMA waits account for those stores
# baseline (speedup 1.0000x reference)
.LBB0_164:
	v_or_b32_e32 v128, s10, v140
	v_lshl_add_u32 v131, v137, 6, v128
	v_lshlrev_b32_e32 v128, 5, v138
	v_lshlrev_b32_e32 v129, 2, v139
	v_or3_b32 v128, v128, v129, s8
	v_cvt_pk_f16_f32 v127, v126, v127
	v_cvt_pk_f16_f32 v126, v124, v125
	v_mov_b64_e32 v[124:125], s[48:49]
	s_movk_i32 s6, 0x1a00
	v_ashrrev_i32_e32 v129, 31, v128
	v_cvt_pk_f16_f32 v107, v106, v107
	v_cvt_pk_f16_f32 v106, v104, v105
	v_or_b32_e32 v104, 48, v131
	v_lshlrev_b64 v[128:129], 1, v[128:129]
	v_cvt_pk_f16_f32 v95, v94, v95
	v_cvt_pk_f16_f32 v94, v92, v93
	v_mad_i64_i32 v[92:93], s[4:5], v104, s6, v[124:125]
	v_lshl_add_u64 v[92:93], v[92:93], 0, v[128:129]
	v_cvt_pk_f16_f32 v55, v54, v55
	v_cvt_pk_f16_f32 v54, v52, v53
	global_store_dwordx2 v[92:93], v[54:55], off offset:288
	v_add_u32_e32 v54, 0x80, v131
	v_mad_i64_i32 v[54:55], s[4:5], v54, s6, v[124:125]
	v_mad_i64_i32 v[132:133], s[4:5], v131, s6, v[124:125]
	v_cvt_pk_f16_f32 v53, v78, v79
	v_cvt_pk_f16_f32 v52, v76, v77
	v_lshl_add_u64 v[54:55], v[54:55], 0, v[128:129]
	v_lshl_add_u64 v[132:133], v[132:133], 0, v[128:129]
	v_cvt_pk_f16_f32 v123, v122, v123
	v_cvt_pk_f16_f32 v122, v120, v121
	v_or_b32_e32 v120, 16, v131
	v_cvt_pk_f16_f32 v115, v114, v115
	v_cvt_pk_f16_f32 v114, v112, v113
	v_or_b32_e32 v112, 32, v131
	v_cvt_pk_f16_f32 v87, v86, v87
	v_cvt_pk_f16_f32 v86, v84, v85
	v_cvt_pk_f16_f32 v85, v102, v103
	v_cvt_pk_f16_f32 v84, v100, v101
	v_cvt_pk_f16_f32 v63, v62, v63
	v_cvt_pk_f16_f32 v62, v60, v61
	global_store_dwordx2 v[54:55], v[52:53], off
	v_cvt_pk_f16_f32 v53, v66, v67
	v_cvt_pk_f16_f32 v52, v64, v65
	v_add_u32_e32 v60, 0x90, v131
	v_cvt_pk_f16_f32 v51, v50, v51
	v_cvt_pk_f16_f32 v50, v48, v49
	v_add_u32_e32 v48, 0xa0, v131
	v_cvt_pk_f16_f32 v43, v42, v43
	v_cvt_pk_f16_f32 v42, v40, v41
	v_add_u32_e32 v40, 0xb0, v131
	v_cvt_pk_f16_f32 v119, v118, v119
	v_cvt_pk_f16_f32 v118, v116, v117
	v_mad_i64_i32 v[116:117], s[4:5], v120, s6, v[124:125]
	v_cvt_pk_f16_f32 v111, v110, v111
	v_cvt_pk_f16_f32 v110, v108, v109
	v_mad_i64_i32 v[108:109], s[4:5], v112, s6, v[124:125]
	global_store_dwordx2 v[132:133], v[84:85], off offset:256
	v_cvt_pk_f16_f32 v85, v98, v99
	v_cvt_pk_f16_f32 v84, v96, v97
	global_store_dwordx2 v[54:55], v[52:53], off offset:32
	v_cvt_pk_f16_f32 v52, v56, v57
	v_mad_i64_i32 v[56:57], s[4:5], v60, s6, v[124:125]
	v_cvt_pk_f16_f32 v47, v46, v47
	v_cvt_pk_f16_f32 v46, v44, v45
	v_mad_i64_i32 v[44:45], s[4:5], v48, s6, v[124:125]
	v_cvt_pk_f16_f32 v39, v38, v39
	v_cvt_pk_f16_f32 v38, v36, v37
	v_mad_i64_i32 v[36:37], s[4:5], v40, s6, v[124:125]
	s_cmp_eq_u32 s19, s18
	v_lshl_add_u64 v[116:117], v[116:117], 0, v[128:129]
	v_lshl_add_u64 v[108:109], v[108:109], 0, v[128:129]
	global_store_dwordx2 v[132:133], v[84:85], off offset:288
	v_cvt_pk_f16_f32 v85, v90, v91
	v_cvt_pk_f16_f32 v84, v88, v89
	v_cvt_pk_f16_f32 v83, v82, v83
	v_cvt_pk_f16_f32 v82, v80, v81
	v_cvt_pk_f16_f32 v75, v74, v75
	v_cvt_pk_f16_f32 v74, v72, v73
	v_cvt_pk_f16_f32 v71, v70, v71
	v_cvt_pk_f16_f32 v70, v68, v69
	v_cvt_pk_f16_f32 v53, v58, v59
	v_lshl_add_u64 v[56:57], v[56:57], 0, v[128:129]
	v_lshl_add_u64 v[44:45], v[44:45], 0, v[128:129]
	v_lshl_add_u64 v[36:37], v[36:37], 0, v[128:129]
	v_cvt_pk_f16_f32 v35, v34, v35
	v_cvt_pk_f16_f32 v34, v32, v33
	v_cvt_pk_f16_f32 v31, v30, v31
	v_cvt_pk_f16_f32 v30, v28, v29
	v_cvt_pk_f16_f32 v27, v26, v27
	v_cvt_pk_f16_f32 v26, v24, v25
	v_cvt_pk_f16_f32 v23, v22, v23
	v_cvt_pk_f16_f32 v22, v20, v21
	v_cvt_pk_f16_f32 v19, v18, v19
	v_cvt_pk_f16_f32 v18, v16, v17
	v_cvt_pk_f16_f32 v15, v14, v15
	v_cvt_pk_f16_f32 v14, v12, v13
	v_cvt_pk_f16_f32 v11, v10, v11
	v_cvt_pk_f16_f32 v10, v8, v9
	v_cvt_pk_f16_f32 v7, v6, v7
	v_cvt_pk_f16_f32 v6, v4, v5
	v_cvt_pk_f16_f32 v3, v2, v3
	v_cvt_pk_f16_f32 v2, v0, v1
	s_cselect_b64 s[4:5], -1, 0
	global_store_dwordx2 v[132:133], v[126:127], off
	global_store_dwordx2 v[132:133], v[122:123], off offset:32
	global_store_dwordx2 v[116:117], v[118:119], off
	global_store_dwordx2 v[116:117], v[114:115], off offset:32
	global_store_dwordx2 v[108:109], v[110:111], off
	global_store_dwordx2 v[108:109], v[106:107], off offset:32
	global_store_dwordx2 v[92:93], v[94:95], off
	global_store_dwordx2 v[92:93], v[86:87], off offset:32
	global_store_dwordx2 v[116:117], v[84:85], off offset:256
	global_store_dwordx2 v[116:117], v[82:83], off offset:288
	global_store_dwordx2 v[108:109], v[74:75], off offset:256
	global_store_dwordx2 v[108:109], v[70:71], off offset:288
	global_store_dwordx2 v[92:93], v[62:63], off offset:256
	global_store_dwordx2 v[56:57], v[52:53], off
	global_store_dwordx2 v[56:57], v[50:51], off offset:32
	global_store_dwordx2 v[44:45], v[46:47], off
	global_store_dwordx2 v[44:45], v[42:43], off offset:32
	global_store_dwordx2 v[36:37], v[38:39], off
	global_store_dwordx2 v[36:37], v[34:35], off offset:32
	global_store_dwordx2 v[54:55], v[30:31], off offset:256
	global_store_dwordx2 v[54:55], v[26:27], off offset:288
	global_store_dwordx2 v[56:57], v[22:23], off offset:256
	global_store_dwordx2 v[56:57], v[18:19], off offset:288
	global_store_dwordx2 v[44:45], v[14:15], off offset:256
	global_store_dwordx2 v[44:45], v[10:11], off offset:288
	global_store_dwordx2 v[36:37], v[6:7], off offset:256
	global_store_dwordx2 v[36:37], v[2:3], off offset:288
	s_waitcnt lgkmcnt(0)
	s_barrier

.LBB0_172:
	s_ashr_i32 s5, s7, 31
	s_lshr_b32 s5, s5, 29
	s_add_i32 s5, s7, s5
	s_ashr_i32 s8, s5, 3
	s_and_b32 s5, s5, -8
	s_sub_i32 s5, s7, s5
	s_lshr_b32 s7, s5, 31
	s_or_b32 s7, s7, 0x68
	s_mul_i32 s7, s7, s5
	s_add_i32 s7, s7, s8
	s_mul_hi_i32 s5, s7, 0x4ec4ec4f
	s_lshr_b32 s8, s5, 31
	s_ashr_i32 s14, s5, 5
	s_add_i32 s14, s14, s8
	s_lshl_b32 s5, s14, 3
	s_sub_i32 s8, 64, s5
	s_min_u32 s10, s8, 8
	s_mul_i32 s15, s14, 0x68
	s_sub_i32 s11, s7, s15
	v_cvt_f32_ubyte0_e32 v1, s10
	v_cvt_f32_i32_e32 v0, s11
	v_rcp_iflag_f32_e32 v2, v1
	s_ashr_i32 s8, s11, 30
	v_mov_b32_e32 v136, v130
	s_or_b32 s20, s8, 1
	v_mul_f32_e32 v2, v0, v2
	v_trunc_f32_e32 v2, v2
	v_fma_f32 v0, -v2, v1, v0
	v_cmp_ge_f32_e64 s[8:9], |v0|, v1
	v_cvt_i32_f32_e32 v2, v2
	v_bfe_i32 v1, v136, 27, 1
	v_lshlrev_b32_e32 v141, 4, v136
	v_lshrrev_b32_e32 v1, 22, v1
	v_ashrrev_i32_e32 v0, 31, v136
	v_add_u32_e32 v1, v141, v1
	v_lshrrev_b32_e32 v0, 26, v0
	v_and_b32_e32 v1, 0xfffffc00, v1
	s_and_b64 s[8:9], s[8:9], exec
	v_add_u32_e32 v0, v136, v0
	v_sub_u32_e32 v1, v141, v1
	v_readfirstlane_b32 s9, v2
	v_ashrrev_i32_e32 v0, 6, v0
	v_lshrrev_b32_e32 v2, 4, v1
	v_bitop3_b32 v2, v2, v1, 32 bitop3:0x6c
	v_lshlrev_b32_e32 v1, 3, v0
	v_and_b32_e32 v3, 0x1ffff0, v1
	v_ashrrev_i32_e32 v1, 31, v2
	v_lshrrev_b32_e32 v1, 26, v1
	s_cselect_b32 s8, s20, 0
	v_add_u32_e32 v4, v2, v1
	s_add_i32 s20, s9, s8
	v_ashrrev_i32_e32 v1, 6, v4
	v_and_b32_e32 v4, 0xc0, v4
	s_sext_i32_i8 s8, s20
	s_mul_i32 s20, s20, s10
	v_sub_u32_e32 v2, v2, v4
	s_sub_i32 s9, s11, s20
	v_lshlrev_b32_e32 v5, 5, v0
	v_ashrrev_i16_sdwa v2, v225, sext(v2) dst_sel:DWORD dst_unused:UNUSED_PAD src0_sel:DWORD src1_sel:BYTE_0
	s_sext_i32_i8 s9, s9
	v_and_b32_e32 v5, 32, v5
	v_bfe_i32 v2, v2, 0, 16
	s_add_i32 s5, s5, s9
	v_add_u32_e32 v4, v5, v2
	v_add_lshl_u32 v3, v1, v3, 11
	v_add_u32_e32 v135, 16, v141
	s_lshl_b32 s10, s5, 8
	s_lshl_b32 s8, s8, 8
	v_lshl_add_u32 v194, v4, 1, v3
	s_andn2_b64 vcc, exec, s[12:13]
	v_add_u32_e32 v134, 0x2000, v135
	v_add_u32_e32 v133, s75, v141
	v_add_u32_e32 v132, 0x4000, v135
	v_add_u32_e32 v131, 0x6000, v135
	s_mov_b32 s100, 1
	s_cbranch_vccnz .LBB0_174
	s_mov_b32 s100, 0
	s_ashr_i32 s9, s8, 31
	s_lshl_b64 s[12:13], s[8:9], 11
	s_add_u32 s12, s16, s12
	s_addc_u32 s13, s17, s13
	s_add_i32 s5, 16, 0x10000
	v_add_u32_e32 v3, s5, v141
	s_ashr_i32 s11, s10, 31
	v_readfirstlane_b32 s5, v3
	s_mov_b32 m0, s5
	v_add_u32_e32 v3, 0x2000, v3
	v_lshl_add_u64 v[4:5], s[12:13], 0, v[194:195]
	global_load_lds_dwordx4 v194, s[12:13]
	s_mov_b64 s[26:27], 0x20000
	v_readfirstlane_b32 s5, v3
	s_lshl_b64 s[12:13], s[10:11], 11
	v_lshl_add_u64 v[4:5], v[4:5], 0, s[26:27]
	s_mov_b32 m0, s5
	s_add_u32 s12, s96, s12
	v_readfirstlane_b32 s5, v135
	global_load_lds_dwordx4 v[4:5], off
	s_addc_u32 s13, s97, s13
	s_mov_b32 m0, s5
	v_lshl_add_u64 v[4:5], s[12:13], 0, v[194:195]
	global_load_lds_dwordx4 v194, s[12:13]
	s_or_b32 s12, s8, 0x80
	s_ashr_i32 s13, s12, 31
	v_readfirstlane_b32 s5, v134
	s_lshl_b64 s[12:13], s[12:13], 11
	v_lshl_add_u64 v[4:5], v[4:5], 0, s[26:27]
	s_mov_b32 m0, s5
	s_add_u32 s12, s16, s12
	v_readfirstlane_b32 s5, v133
	global_load_lds_dwordx4 v[4:5], off
	s_addc_u32 s13, s17, s13
	s_mov_b32 m0, s5
	v_lshl_add_u64 v[4:5], s[12:13], 0, v[194:195]
	global_load_lds_dwordx4 v194, s[12:13]
	s_or_b32 s12, s10, 0x80
	s_ashr_i32 s13, s12, 31
	v_add_u32_e32 v3, 0x2000, v133
	s_lshl_b64 s[12:13], s[12:13], 11
	v_readfirstlane_b32 s5, v3
	s_add_u32 s12, s96, s12
	v_lshl_add_u64 v[4:5], v[4:5], 0, s[26:27]
	s_mov_b32 m0, s5
	s_addc_u32 s13, s97, s13
	v_readfirstlane_b32 s5, v132
	global_load_lds_dwordx4 v[4:5], off
	v_lshl_add_u64 v[4:5], s[12:13], 0, v[194:195]
	s_mov_b32 m0, s5
	v_readfirstlane_b32 s5, v131
	global_load_lds_dwordx4 v194, s[12:13]
	v_lshl_add_u64 v[4:5], v[4:5], 0, s[26:27]
	s_mov_b32 m0, s5
	s_nop 0
	global_load_lds_dwordx4 v[4:5], off

.LBB0_176:
	s_or_b64 exec, exec, s[12:13]
	s_ashr_i32 s9, s8, 31
	v_and_b32_e32 v140, 15, v136
	s_lshl_b64 s[12:13], s[8:9], 11
	v_bfe_u32 v139, v136, 4, 2
	v_lshlrev_b32_e32 v3, 6, v140
	v_lshlrev_b32_e32 v4, 2, v136
	s_add_u32 s26, s16, s12
	v_bfe_u32 v138, v136, 6, 2
	v_lshl_or_b32 v3, v139, 4, v3
	v_and_b32_e32 v4, 32, v4
	v_lshlrev_b32_e32 v5, 13, v137
	s_addc_u32 s27, s17, s13
	s_add_i32 s5, 16, 0x18000
	v_bitop3_b32 v8, v3, v5, v4 bitop3:0xde
	v_lshlrev_b32_e32 v5, 12, v138
	v_add_u32_e32 v144, s5, v141
	s_ashr_i32 s11, s10, 31
	v_bitop3_b32 v143, v3, v5, v4 bitop3:0xde
	v_lshl_add_u64 v[4:5], s[26:27], 0, v[194:195]
	s_mov_b64 s[28:29], 0x80
	v_readfirstlane_b32 s9, v144
	v_add_u32_e32 v145, 0x2000, v144
	s_lshl_b64 s[26:27], s[10:11], 11
	v_lshl_add_u64 v[6:7], v[4:5], 0, s[28:29]
	s_mov_b32 m0, s9
	s_mov_b64 s[30:31], 0x20080
	v_readfirstlane_b32 s9, v145
	s_cmp_eq_u32 s100, 0
	s_cbranch_scc1 .Lnw1a_a
	s_waitcnt vmcnt(36)
	s_branch .Lnw1a_b
.Lnw1a_a:
	s_waitcnt vmcnt(4)
.Lnw1a_b:
	s_add_u32 s26, s96, s26
	s_barrier
	global_load_lds_dwordx4 v[6:7], off
	v_lshl_add_u64 v[4:5], v[4:5], 0, s[30:31]
	s_mov_b32 m0, s9
	s_addc_u32 s27, s97, s27
	global_load_lds_dwordx4 v[4:5], off
	v_lshl_add_u64 v[4:5], s[26:27], 0, v[194:195]
	s_or_b32 s26, s8, 0x80
	v_add_u32_e32 v146, 0x8000, v135
	s_ashr_i32 s27, s26, 31
	v_readfirstlane_b32 s9, v146
	v_add_u32_e32 v147, 0xa000, v135
	s_lshl_b64 s[26:27], s[26:27], 11
	v_lshl_add_u64 v[6:7], v[4:5], 0, s[28:29]
	s_mov_b32 m0, s9
	v_readfirstlane_b32 s9, v147
	s_add_u32 s26, s16, s26
	global_load_lds_dwordx4 v[6:7], off
	v_lshl_add_u64 v[4:5], v[4:5], 0, s[30:31]
	s_mov_b32 m0, s9
	s_addc_u32 s27, s17, s27
	v_add_u32_e32 v148, s2, v141
	global_load_lds_dwordx4 v[4:5], off
	v_lshl_add_u64 v[4:5], s[26:27], 0, v[194:195]
	v_readfirstlane_b32 s9, v148
	v_add_u32_e32 v149, 0x2000, v148
	v_lshl_add_u64 v[6:7], v[4:5], 0, s[28:29]
	s_mov_b32 m0, s9
	v_readfirstlane_b32 s9, v149
	global_load_lds_dwordx4 v[6:7], off
	v_lshl_add_u64 v[4:5], v[4:5], 0, s[30:31]
	s_mov_b32 m0, s9
	s_add_u32 s12, s24, s12
	global_load_lds_dwordx4 v[4:5], off
	s_addc_u32 s13, s25, s13
	s_sub_i32 s7, s7, s20
	s_sub_i32 s7, s7, s15
	s_sext_i32_i8 s7, s7
	v_lshlrev_b32_e32 v3, 14, v0
	s_lshl_b32 s9, s14, 11
	s_lshl_b32 s7, s7, 8
	v_and_b32_e32 v3, 0xffff8000, v3
	s_add_i32 s14, s9, s7
	v_lshl_add_u32 v1, v1, 11, v3
	v_and_b32_e32 v0, 1, v0
	s_ashr_i32 s15, s14, 31
	s_cmp_eq_u32 s100, 0
	s_cbranch_scc1 .Lnw1b_a
	s_waitcnt vmcnt(38)
	s_branch .Lnw1b_b
.Lnw1b_a:
	s_waitcnt vmcnt(6)
.Lnw1b_b:
	v_lshl_or_b32 v0, v0, 6, v1
	s_lshl_b64 s[14:15], s[14:15], 11
	v_lshl_add_u32 v128, v2, 1, v0
	s_add_u32 s14, s46, s14
	v_mov_b32_e32 v0, 0
	v_mov_b32_e32 v129, v195
	s_addc_u32 s15, s47, s15
	s_mov_b32 s7, -2
	v_add_u32_e32 v142, 16, v8
	v_mov_b32_e32 v1, v0
	v_mov_b32_e32 v2, v0
	v_mov_b32_e32 v3, v0
	v_mov_b32_e32 v4, v0
	v_mov_b32_e32 v5, v0
	v_mov_b32_e32 v6, v0
	v_mov_b32_e32 v7, v0
	v_mov_b32_e32 v8, v0
	v_mov_b32_e32 v9, v0
	v_mov_b32_e32 v10, v0
	v_mov_b32_e32 v11, v0
	v_mov_b32_e32 v12, v0
	v_mov_b32_e32 v13, v0
	v_mov_b32_e32 v14, v0
	v_mov_b32_e32 v15, v0
	v_mov_b32_e32 v16, v0
	v_mov_b32_e32 v17, v0
	v_mov_b32_e32 v18, v0
	v_mov_b32_e32 v19, v0
	v_mov_b32_e32 v20, v0
	v_mov_b32_e32 v21, v0
	v_mov_b32_e32 v22, v0
	v_mov_b32_e32 v23, v0
	v_mov_b32_e32 v24, v0
	v_mov_b32_e32 v25, v0
	v_mov_b32_e32 v26, v0
	v_mov_b32_e32 v27, v0
	v_mov_b32_e32 v28, v0
	v_mov_b32_e32 v29, v0
	v_mov_b32_e32 v30, v0
	v_mov_b32_e32 v31, v0
	v_mov_b32_e32 v32, v0
	v_mov_b32_e32 v33, v0
	v_mov_b32_e32 v34, v0
	v_mov_b32_e32 v35, v0
	v_mov_b32_e32 v36, v0
	v_mov_b32_e32 v37, v0
	v_mov_b32_e32 v38, v0
	v_mov_b32_e32 v39, v0
	v_mov_b32_e32 v40, v0
	v_mov_b32_e32 v41, v0
	v_mov_b32_e32 v42, v0
	v_mov_b32_e32 v43, v0
	v_mov_b32_e32 v44, v0
	v_mov_b32_e32 v45, v0
	v_mov_b32_e32 v46, v0
	v_mov_b32_e32 v47, v0
	v_mov_b32_e32 v48, v0
	v_mov_b32_e32 v49, v0
	v_mov_b32_e32 v50, v0
	v_mov_b32_e32 v51, v0
	v_mov_b32_e32 v52, v0
	v_mov_b32_e32 v53, v0
	v_mov_b32_e32 v54, v0
	v_mov_b32_e32 v55, v0
	v_mov_b32_e32 v56, v0
	v_mov_b32_e32 v57, v0
	v_mov_b32_e32 v58, v0
	v_mov_b32_e32 v59, v0
	v_mov_b32_e32 v60, v0
	v_mov_b32_e32 v61, v0
	v_mov_b32_e32 v62, v0
	v_mov_b32_e32 v63, v0
	v_mov_b32_e32 v64, v0
	v_mov_b32_e32 v65, v0
	v_mov_b32_e32 v66, v0
	v_mov_b32_e32 v67, v0
	v_mov_b32_e32 v68, v0
	v_mov_b32_e32 v69, v0
	v_mov_b32_e32 v70, v0
	v_mov_b32_e32 v71, v0
	v_mov_b32_e32 v72, v0
	v_mov_b32_e32 v73, v0
	v_mov_b32_e32 v74, v0
	v_mov_b32_e32 v75, v0
	v_mov_b32_e32 v76, v0
	v_mov_b32_e32 v77, v0
	v_mov_b32_e32 v78, v0
	v_mov_b32_e32 v79, v0
	v_mov_b32_e32 v80, v0
	v_mov_b32_e32 v81, v0
	v_mov_b32_e32 v82, v0
	v_mov_b32_e32 v83, v0
	v_mov_b32_e32 v84, v0
	v_mov_b32_e32 v85, v0
	v_mov_b32_e32 v86, v0
	v_mov_b32_e32 v87, v0
	v_mov_b32_e32 v88, v0
	v_mov_b32_e32 v89, v0
	v_mov_b32_e32 v90, v0
	v_mov_b32_e32 v91, v0
	v_mov_b32_e32 v92, v0
	v_mov_b32_e32 v93, v0
	v_mov_b32_e32 v94, v0
	v_mov_b32_e32 v95, v0
	v_mov_b32_e32 v96, v0
	v_mov_b32_e32 v97, v0
	v_mov_b32_e32 v98, v0
	v_mov_b32_e32 v99, v0
	v_mov_b32_e32 v100, v0
	v_mov_b32_e32 v101, v0
	v_mov_b32_e32 v102, v0
	v_mov_b32_e32 v103, v0
	v_mov_b32_e32 v104, v0
	v_mov_b32_e32 v105, v0
	v_mov_b32_e32 v106, v0
	v_mov_b32_e32 v107, v0
	v_mov_b32_e32 v108, v0
	v_mov_b32_e32 v109, v0
	v_mov_b32_e32 v110, v0
	v_mov_b32_e32 v111, v0
	v_mov_b32_e32 v112, v0
	v_mov_b32_e32 v113, v0
	v_mov_b32_e32 v114, v0
	v_mov_b32_e32 v115, v0
	v_mov_b32_e32 v116, v0
	v_mov_b32_e32 v117, v0
	v_mov_b32_e32 v118, v0
	v_mov_b32_e32 v119, v0
	v_mov_b32_e32 v120, v0
	v_mov_b32_e32 v121, v0
	v_mov_b32_e32 v122, v0
	v_mov_b32_e32 v123, v0
	v_mov_b32_e32 v124, v0
	v_mov_b32_e32 v125, v0
	v_mov_b32_e32 v126, v0
	v_mov_b32_e32 v127, v0
	s_mov_b64 s[20:21], 0x3240080
	s_mov_b64 s[26:27], 0x3260080
	s_mov_b64 s[28:29], 0x1600100
	s_mov_b64 s[30:31], 0x1620100
	s_mov_b64 s[34:35], 0x3200100
	s_mov_b64 s[36:37], 0x3220100
	s_mov_b64 s[38:39], 0x1640100
	s_mov_b64 s[40:41], 0x1660100
	s_mov_b64 s[42:43], 0x3240100
	s_mov_b64 s[44:45], 0x3260100
	s_mov_b64 s[86:87], 0x1600180
	s_mov_b64 s[94:95], 0x1620180
	s_mov_b64 vcc, 0x3200180
	s_mov_b64 s[22:23], 0x3220180
	s_mov_b64 s[56:57], 0x1640180
	s_mov_b64 s[76:77], 0x1660180
	s_barrier

.LBB0_1753:
	v_lshlrev_b32_e32 v129, 5, v138
	v_lshlrev_b32_e32 v131, 2, v139
	s_lshl_b32 s4, s24, 7
	v_or3_b32 v132, v129, v131, s4
	v_mul_f32_e32 v129, 0xbfb8aa3b, v120
	v_exp_f32_e32 v129, v129
	v_or_b32_e32 v128, s14, v140
	v_lshl_add_u32 v128, v137, 6, v128
	s_movk_i32 s12, 0x1600
	v_add_f32_e32 v129, 1.0, v129
	v_rcp_f32_e32 v134, v129
	v_mul_f32_e32 v129, 0xbfb8aa3b, v121
	v_exp_f32_e32 v129, v129
	v_ashrrev_i32_e32 v133, 31, v132
	s_cmp_eq_u32 s23, s22
	v_mov_b32_e32 v225, v196
	v_add_f32_e32 v129, 1.0, v129
	v_rcp_f32_e32 v135, v129
	s_nop 0
	v_pk_mul_f32 v[120:121], v[120:121], v[134:135]
	s_nop 0
	v_pk_mul_f32 v[120:121], v[120:121], v[124:125]
	s_nop 0
	v_cvt_pk_f16_f32 v124, v120, v121
	v_mul_f32_e32 v120, 0xbfb8aa3b, v122
	v_mul_f32_e32 v121, 0xbfb8aa3b, v123
	v_exp_f32_e32 v120, v120
	v_exp_f32_e32 v121, v121
	v_add_f32_e32 v120, 1.0, v120
	v_add_f32_e32 v121, 1.0, v121
	v_rcp_f32_e32 v120, v120
	v_rcp_f32_e32 v121, v121
	s_nop 0
	v_pk_mul_f32 v[120:121], v[122:123], v[120:121]
	s_nop 0
	v_pk_mul_f32 v[120:121], v[120:121], v[126:127]
	v_lshlrev_b64 v[122:123], 1, v[132:133]
	v_cvt_pk_f16_f32 v125, v120, v121
	v_mov_b64_e32 v[120:121], s[48:49]
	v_mad_i64_i32 v[126:127], s[4:5], v128, s12, v[120:121]
	v_lshl_add_u64 v[126:127], v[126:127], 0, v[122:123]
	global_store_dwordx2 v[126:127], v[124:125], off
	v_mul_f32_e32 v124, 0xbfb8aa3b, v112
	v_mul_f32_e32 v125, 0xbfb8aa3b, v113
	v_exp_f32_e32 v124, v124
	v_exp_f32_e32 v125, v125
	v_add_f32_e32 v124, 1.0, v124
	v_add_f32_e32 v125, 1.0, v125
	v_rcp_f32_e32 v124, v124
	v_rcp_f32_e32 v125, v125
	s_nop 0
	v_pk_mul_f32 v[112:113], v[112:113], v[124:125]
	s_nop 0
	v_pk_mul_f32 v[112:113], v[112:113], v[116:117]
	s_nop 0
	v_cvt_pk_f16_f32 v112, v112, v113
	v_mul_f32_e32 v113, 0xbfb8aa3b, v114
	v_exp_f32_e32 v113, v113
	s_nop 0
	v_add_f32_e32 v113, 1.0, v113
	v_rcp_f32_e32 v116, v113
	v_mul_f32_e32 v113, 0xbfb8aa3b, v115
	v_exp_f32_e32 v113, v113
	s_nop 0
	v_add_f32_e32 v113, 1.0, v113
	v_rcp_f32_e32 v117, v113
	s_nop 0
	v_pk_mul_f32 v[114:115], v[114:115], v[116:117]
	s_nop 0
	v_pk_mul_f32 v[114:115], v[114:115], v[118:119]
	s_nop 0
	v_cvt_pk_f16_f32 v113, v114, v115
	global_store_dwordx2 v[126:127], v[112:113], off offset:32
	v_mul_f32_e32 v112, 0xbfb8aa3b, v104
	v_mul_f32_e32 v113, 0xbfb8aa3b, v105
	v_exp_f32_e32 v112, v112
	v_exp_f32_e32 v113, v113
	v_or_b32_e32 v114, 16, v128
	v_add_f32_e32 v112, 1.0, v112
	v_add_f32_e32 v113, 1.0, v113
	v_rcp_f32_e32 v112, v112
	v_rcp_f32_e32 v113, v113
	s_nop 0
	v_pk_mul_f32 v[104:105], v[104:105], v[112:113]
	s_nop 0
	v_pk_mul_f32 v[104:105], v[104:105], v[108:109]
	s_nop 0
	v_cvt_pk_f16_f32 v104, v104, v105
	v_mul_f32_e32 v105, 0xbfb8aa3b, v106
	v_exp_f32_e32 v105, v105
	s_nop 0
	v_add_f32_e32 v105, 1.0, v105
	v_rcp_f32_e32 v108, v105
	v_mul_f32_e32 v105, 0xbfb8aa3b, v107
	v_exp_f32_e32 v105, v105
	s_nop 0
	v_add_f32_e32 v105, 1.0, v105
	v_rcp_f32_e32 v109, v105
	s_nop 0
	v_pk_mul_f32 v[106:107], v[106:107], v[108:109]
	s_nop 0
	v_pk_mul_f32 v[106:107], v[106:107], v[110:111]
	s_nop 0
	v_cvt_pk_f16_f32 v105, v106, v107
	v_mad_i64_i32 v[106:107], s[4:5], v114, s12, v[120:121]
	v_lshl_add_u64 v[106:107], v[106:107], 0, v[122:123]
	global_store_dwordx2 v[106:107], v[104:105], off
	v_mul_f32_e32 v104, 0xbfb8aa3b, v96
	v_mul_f32_e32 v105, 0xbfb8aa3b, v97
	v_exp_f32_e32 v104, v104
	v_exp_f32_e32 v105, v105
	v_add_f32_e32 v104, 1.0, v104
	v_add_f32_e32 v105, 1.0, v105
	v_rcp_f32_e32 v104, v104
	v_rcp_f32_e32 v105, v105
	s_nop 0
	v_pk_mul_f32 v[96:97], v[96:97], v[104:105]
	s_nop 0
	v_pk_mul_f32 v[96:97], v[96:97], v[100:101]
	s_nop 0
	v_cvt_pk_f16_f32 v96, v96, v97
	v_mul_f32_e32 v97, 0xbfb8aa3b, v98
	v_exp_f32_e32 v97, v97
	s_nop 0
	v_add_f32_e32 v97, 1.0, v97
	v_rcp_f32_e32 v100, v97
	v_mul_f32_e32 v97, 0xbfb8aa3b, v99
	v_exp_f32_e32 v97, v97
	s_nop 0
	v_add_f32_e32 v97, 1.0, v97
	v_rcp_f32_e32 v101, v97
	s_nop 0
	v_pk_mul_f32 v[98:99], v[98:99], v[100:101]
	s_nop 0
	v_pk_mul_f32 v[98:99], v[98:99], v[102:103]
	s_nop 0
	v_cvt_pk_f16_f32 v97, v98, v99
	global_store_dwordx2 v[106:107], v[96:97], off offset:32
	v_mul_f32_e32 v96, 0xbfb8aa3b, v88
	v_mul_f32_e32 v97, 0xbfb8aa3b, v89
	v_exp_f32_e32 v96, v96
	v_exp_f32_e32 v97, v97
	v_or_b32_e32 v98, 32, v128
	v_add_f32_e32 v96, 1.0, v96
	v_add_f32_e32 v97, 1.0, v97
	v_rcp_f32_e32 v96, v96
	v_rcp_f32_e32 v97, v97
	s_nop 0
	v_pk_mul_f32 v[88:89], v[88:89], v[96:97]
	s_nop 0
	v_pk_mul_f32 v[88:89], v[88:89], v[92:93]
	s_nop 0
	v_cvt_pk_f16_f32 v88, v88, v89
	v_mul_f32_e32 v89, 0xbfb8aa3b, v90
	v_exp_f32_e32 v89, v89
	s_nop 0
	v_add_f32_e32 v89, 1.0, v89
	v_rcp_f32_e32 v92, v89
	v_mul_f32_e32 v89, 0xbfb8aa3b, v91
	v_exp_f32_e32 v89, v89
	s_nop 0
	v_add_f32_e32 v89, 1.0, v89
	v_rcp_f32_e32 v93, v89
	s_nop 0
	v_pk_mul_f32 v[90:91], v[90:91], v[92:93]
	s_nop 0
	v_pk_mul_f32 v[90:91], v[90:91], v[94:95]
	s_nop 0
	v_cvt_pk_f16_f32 v89, v90, v91
	v_mad_i64_i32 v[90:91], s[4:5], v98, s12, v[120:121]
	v_lshl_add_u64 v[90:91], v[90:91], 0, v[122:123]
	global_store_dwordx2 v[90:91], v[88:89], off
	v_mul_f32_e32 v88, 0xbfb8aa3b, v80
	v_mul_f32_e32 v89, 0xbfb8aa3b, v81
	v_exp_f32_e32 v88, v88
	v_exp_f32_e32 v89, v89
	v_add_f32_e32 v88, 1.0, v88
	v_add_f32_e32 v89, 1.0, v89
	v_rcp_f32_e32 v88, v88
	v_rcp_f32_e32 v89, v89
	s_nop 0
	v_pk_mul_f32 v[80:81], v[80:81], v[88:89]
	s_nop 0
	v_pk_mul_f32 v[80:81], v[80:81], v[84:85]
	s_nop 0
	v_cvt_pk_f16_f32 v80, v80, v81
	v_mul_f32_e32 v81, 0xbfb8aa3b, v82
	v_exp_f32_e32 v81, v81
	s_nop 0
	v_add_f32_e32 v81, 1.0, v81
	v_rcp_f32_e32 v84, v81
	v_mul_f32_e32 v81, 0xbfb8aa3b, v83
	v_exp_f32_e32 v81, v81
	s_nop 0
	v_add_f32_e32 v81, 1.0, v81
	v_rcp_f32_e32 v85, v81
	s_nop 0
	v_pk_mul_f32 v[82:83], v[82:83], v[84:85]
	s_nop 0
	v_pk_mul_f32 v[82:83], v[82:83], v[86:87]
	s_nop 0
	v_cvt_pk_f16_f32 v81, v82, v83
	global_store_dwordx2 v[90:91], v[80:81], off offset:32
	v_mul_f32_e32 v80, 0xbfb8aa3b, v72
	v_mul_f32_e32 v81, 0xbfb8aa3b, v73
	v_exp_f32_e32 v80, v80
	v_exp_f32_e32 v81, v81
	v_or_b32_e32 v82, 48, v128
	v_add_f32_e32 v80, 1.0, v80
	v_add_f32_e32 v81, 1.0, v81
	v_rcp_f32_e32 v80, v80
	v_rcp_f32_e32 v81, v81
	s_nop 0
	v_pk_mul_f32 v[72:73], v[72:73], v[80:81]
	s_nop 0
	v_pk_mul_f32 v[72:73], v[72:73], v[76:77]
	s_nop 0
	v_cvt_pk_f16_f32 v72, v72, v73
	v_mul_f32_e32 v73, 0xbfb8aa3b, v74
	v_exp_f32_e32 v73, v73
	s_nop 0
	v_add_f32_e32 v73, 1.0, v73
	v_rcp_f32_e32 v76, v73
	v_mul_f32_e32 v73, 0xbfb8aa3b, v75
	v_exp_f32_e32 v73, v73
	s_nop 0
	v_add_f32_e32 v73, 1.0, v73
	v_rcp_f32_e32 v77, v73
	s_nop 0
	v_pk_mul_f32 v[74:75], v[74:75], v[76:77]
	s_nop 0
	v_pk_mul_f32 v[74:75], v[74:75], v[78:79]
	s_nop 0
	v_cvt_pk_f16_f32 v73, v74, v75
	v_mad_i64_i32 v[74:75], s[4:5], v82, s12, v[120:121]
	v_lshl_add_u64 v[74:75], v[74:75], 0, v[122:123]
	global_store_dwordx2 v[74:75], v[72:73], off
	v_mul_f32_e32 v72, 0xbfb8aa3b, v64
	v_mul_f32_e32 v73, 0xbfb8aa3b, v65
	v_exp_f32_e32 v72, v72
	v_exp_f32_e32 v73, v73
	v_add_f32_e32 v72, 1.0, v72
	v_add_f32_e32 v73, 1.0, v73
	v_rcp_f32_e32 v72, v72
	v_rcp_f32_e32 v73, v73
	s_nop 0
	v_pk_mul_f32 v[64:65], v[64:65], v[72:73]
	s_nop 0
	v_pk_mul_f32 v[64:65], v[64:65], v[68:69]
	s_nop 0
	v_cvt_pk_f16_f32 v64, v64, v65
	v_mul_f32_e32 v65, 0xbfb8aa3b, v66
	v_exp_f32_e32 v65, v65
	s_nop 0
	v_add_f32_e32 v65, 1.0, v65
	v_rcp_f32_e32 v68, v65
	v_mul_f32_e32 v65, 0xbfb8aa3b, v67
	v_exp_f32_e32 v65, v65
	s_nop 0
	v_add_f32_e32 v65, 1.0, v65
	v_rcp_f32_e32 v69, v65
	s_nop 0
	v_pk_mul_f32 v[66:67], v[66:67], v[68:69]
	s_nop 0
	v_pk_mul_f32 v[66:67], v[66:67], v[70:71]
	s_nop 0
	v_cvt_pk_f16_f32 v65, v66, v67
	global_store_dwordx2 v[74:75], v[64:65], off offset:32
	v_mul_f32_e32 v64, 0xbfb8aa3b, v56
	v_mul_f32_e32 v65, 0xbfb8aa3b, v57
	v_exp_f32_e32 v64, v64
	v_exp_f32_e32 v65, v65
	v_add_u32_e32 v66, 0x80, v128
	v_add_f32_e32 v64, 1.0, v64
	v_add_f32_e32 v65, 1.0, v65
	v_rcp_f32_e32 v64, v64
	v_rcp_f32_e32 v65, v65
	s_nop 0
	v_pk_mul_f32 v[56:57], v[56:57], v[64:65]
	s_nop 0
	v_pk_mul_f32 v[56:57], v[56:57], v[60:61]
	s_nop 0
	v_cvt_pk_f16_f32 v56, v56, v57
	v_mul_f32_e32 v57, 0xbfb8aa3b, v58
	v_exp_f32_e32 v57, v57
	s_nop 0
	v_add_f32_e32 v57, 1.0, v57
	v_rcp_f32_e32 v60, v57
	v_mul_f32_e32 v57, 0xbfb8aa3b, v59
	v_exp_f32_e32 v57, v57
	s_nop 0
	v_add_f32_e32 v57, 1.0, v57
	v_rcp_f32_e32 v61, v57
	s_nop 0
	v_pk_mul_f32 v[58:59], v[58:59], v[60:61]
	s_nop 0
	v_pk_mul_f32 v[58:59], v[58:59], v[62:63]
	s_nop 0
	v_cvt_pk_f16_f32 v57, v58, v59
	v_mad_i64_i32 v[58:59], s[4:5], v66, s12, v[120:121]
	v_lshl_add_u64 v[58:59], v[58:59], 0, v[122:123]
	global_store_dwordx2 v[58:59], v[56:57], off
	v_mul_f32_e32 v56, 0xbfb8aa3b, v48
	v_mul_f32_e32 v57, 0xbfb8aa3b, v49
	v_exp_f32_e32 v56, v56
	v_exp_f32_e32 v57, v57
	v_add_f32_e32 v56, 1.0, v56
	v_add_f32_e32 v57, 1.0, v57
	v_rcp_f32_e32 v56, v56
	v_rcp_f32_e32 v57, v57
	s_nop 0
	v_pk_mul_f32 v[48:49], v[48:49], v[56:57]
	s_nop 0
	v_pk_mul_f32 v[48:49], v[48:49], v[52:53]
	s_nop 0
	v_cvt_pk_f16_f32 v48, v48, v49
	v_mul_f32_e32 v49, 0xbfb8aa3b, v50
	v_exp_f32_e32 v49, v49
	s_nop 0
	v_add_f32_e32 v49, 1.0, v49
	v_rcp_f32_e32 v52, v49
	v_mul_f32_e32 v49, 0xbfb8aa3b, v51
	v_exp_f32_e32 v49, v49
	s_nop 0
	v_add_f32_e32 v49, 1.0, v49
	v_rcp_f32_e32 v53, v49
	s_nop 0
	v_pk_mul_f32 v[50:51], v[50:51], v[52:53]
	s_nop 0
	v_pk_mul_f32 v[50:51], v[50:51], v[54:55]
	s_nop 0
	v_cvt_pk_f16_f32 v49, v50, v51
	global_store_dwordx2 v[58:59], v[48:49], off offset:32
	v_mul_f32_e32 v48, 0xbfb8aa3b, v40
	v_mul_f32_e32 v49, 0xbfb8aa3b, v41
	v_exp_f32_e32 v48, v48
	v_exp_f32_e32 v49, v49
	v_add_u32_e32 v50, 0x90, v128
	v_add_f32_e32 v48, 1.0, v48
	v_add_f32_e32 v49, 1.0, v49
	v_rcp_f32_e32 v48, v48
	v_rcp_f32_e32 v49, v49
	s_nop 0
	v_pk_mul_f32 v[40:41], v[40:41], v[48:49]
	s_nop 0
	v_pk_mul_f32 v[40:41], v[40:41], v[44:45]
	s_nop 0
	v_cvt_pk_f16_f32 v40, v40, v41
	v_mul_f32_e32 v41, 0xbfb8aa3b, v42
	v_exp_f32_e32 v41, v41
	s_nop 0
	v_add_f32_e32 v41, 1.0, v41
	v_rcp_f32_e32 v44, v41
	v_mul_f32_e32 v41, 0xbfb8aa3b, v43
	v_exp_f32_e32 v41, v41
	s_nop 0
	v_add_f32_e32 v41, 1.0, v41
	v_rcp_f32_e32 v45, v41
	s_nop 0
	v_pk_mul_f32 v[42:43], v[42:43], v[44:45]
	s_nop 0
	v_pk_mul_f32 v[42:43], v[42:43], v[46:47]
	s_nop 0
	v_cvt_pk_f16_f32 v41, v42, v43
	v_mad_i64_i32 v[42:43], s[4:5], v50, s12, v[120:121]
	v_lshl_add_u64 v[42:43], v[42:43], 0, v[122:123]
	global_store_dwordx2 v[42:43], v[40:41], off
	v_mul_f32_e32 v40, 0xbfb8aa3b, v32
	v_mul_f32_e32 v41, 0xbfb8aa3b, v33
	v_exp_f32_e32 v40, v40
	v_exp_f32_e32 v41, v41
	v_add_f32_e32 v40, 1.0, v40
	v_add_f32_e32 v41, 1.0, v41
	v_rcp_f32_e32 v40, v40
	v_rcp_f32_e32 v41, v41
	s_nop 0
	v_pk_mul_f32 v[32:33], v[32:33], v[40:41]
	s_nop 0
	v_pk_mul_f32 v[32:33], v[32:33], v[36:37]
	s_nop 0
	v_cvt_pk_f16_f32 v32, v32, v33
	v_mul_f32_e32 v33, 0xbfb8aa3b, v34
	v_exp_f32_e32 v33, v33
	s_nop 0
	v_add_f32_e32 v33, 1.0, v33
	v_rcp_f32_e32 v36, v33
	v_mul_f32_e32 v33, 0xbfb8aa3b, v35
	v_exp_f32_e32 v33, v33
	s_nop 0
	v_add_f32_e32 v33, 1.0, v33
	v_rcp_f32_e32 v37, v33
	s_nop 0
	v_pk_mul_f32 v[34:35], v[34:35], v[36:37]
	s_nop 0
	v_pk_mul_f32 v[34:35], v[34:35], v[38:39]
	s_nop 0
	v_cvt_pk_f16_f32 v33, v34, v35
	global_store_dwordx2 v[42:43], v[32:33], off offset:32
	v_mul_f32_e32 v32, 0xbfb8aa3b, v24
	v_mul_f32_e32 v33, 0xbfb8aa3b, v25
	v_exp_f32_e32 v32, v32
	v_exp_f32_e32 v33, v33
	v_add_u32_e32 v34, 0xa0, v128
	v_add_f32_e32 v32, 1.0, v32
	v_add_f32_e32 v33, 1.0, v33
	v_rcp_f32_e32 v32, v32
	v_rcp_f32_e32 v33, v33
	s_nop 0
	v_pk_mul_f32 v[24:25], v[24:25], v[32:33]
	s_nop 0
	v_pk_mul_f32 v[24:25], v[24:25], v[28:29]
	s_nop 0
	v_cvt_pk_f16_f32 v24, v24, v25
	v_mul_f32_e32 v25, 0xbfb8aa3b, v26
	v_exp_f32_e32 v25, v25
	s_nop 0
	v_add_f32_e32 v25, 1.0, v25
	v_rcp_f32_e32 v28, v25
	v_mul_f32_e32 v25, 0xbfb8aa3b, v27
	v_exp_f32_e32 v25, v25
	s_nop 0
	v_add_f32_e32 v25, 1.0, v25
	v_rcp_f32_e32 v29, v25
	s_nop 0
	v_pk_mul_f32 v[26:27], v[26:27], v[28:29]
	s_nop 0
	v_pk_mul_f32 v[26:27], v[26:27], v[30:31]
	s_nop 0
	v_cvt_pk_f16_f32 v25, v26, v27
	v_mad_i64_i32 v[26:27], s[4:5], v34, s12, v[120:121]
	v_lshl_add_u64 v[26:27], v[26:27], 0, v[122:123]
	global_store_dwordx2 v[26:27], v[24:25], off
	v_mul_f32_e32 v24, 0xbfb8aa3b, v16
	v_mul_f32_e32 v25, 0xbfb8aa3b, v17
	v_exp_f32_e32 v24, v24
	v_exp_f32_e32 v25, v25
	v_add_f32_e32 v24, 1.0, v24
	v_add_f32_e32 v25, 1.0, v25
	v_rcp_f32_e32 v24, v24
	v_rcp_f32_e32 v25, v25
	s_nop 0
	v_pk_mul_f32 v[16:17], v[16:17], v[24:25]
	s_nop 0
	v_pk_mul_f32 v[16:17], v[16:17], v[20:21]
	s_nop 0
	v_cvt_pk_f16_f32 v16, v16, v17
	v_mul_f32_e32 v17, 0xbfb8aa3b, v18
	v_exp_f32_e32 v17, v17
	s_nop 0
	v_add_f32_e32 v17, 1.0, v17
	v_rcp_f32_e32 v20, v17
	v_mul_f32_e32 v17, 0xbfb8aa3b, v19
	v_exp_f32_e32 v17, v17
	s_nop 0
	v_add_f32_e32 v17, 1.0, v17
	v_rcp_f32_e32 v21, v17
	s_nop 0
	v_pk_mul_f32 v[18:19], v[18:19], v[20:21]
	s_nop 0
	v_pk_mul_f32 v[18:19], v[18:19], v[22:23]
	s_nop 0
	v_cvt_pk_f16_f32 v17, v18, v19
	global_store_dwordx2 v[26:27], v[16:17], off offset:32
	v_mul_f32_e32 v16, 0xbfb8aa3b, v8
	v_mul_f32_e32 v17, 0xbfb8aa3b, v9
	v_exp_f32_e32 v16, v16
	v_exp_f32_e32 v17, v17
	v_add_u32_e32 v18, 0xb0, v128
	v_add_f32_e32 v16, 1.0, v16
	v_add_f32_e32 v17, 1.0, v17
	v_rcp_f32_e32 v16, v16
	v_rcp_f32_e32 v17, v17
	s_nop 0
	v_pk_mul_f32 v[8:9], v[8:9], v[16:17]
	s_nop 0
	v_pk_mul_f32 v[8:9], v[8:9], v[12:13]
	s_nop 0
	v_cvt_pk_f16_f32 v8, v8, v9
	v_mul_f32_e32 v9, 0xbfb8aa3b, v10
	v_exp_f32_e32 v9, v9
	s_nop 0
	v_add_f32_e32 v9, 1.0, v9
	v_rcp_f32_e32 v12, v9
	v_mul_f32_e32 v9, 0xbfb8aa3b, v11
	v_exp_f32_e32 v9, v9
	s_nop 0
	v_add_f32_e32 v9, 1.0, v9
	v_rcp_f32_e32 v13, v9
	s_nop 0
	v_pk_mul_f32 v[10:11], v[10:11], v[12:13]
	s_nop 0
	v_pk_mul_f32 v[10:11], v[10:11], v[14:15]
	s_nop 0
	v_cvt_pk_f16_f32 v9, v10, v11
	v_mad_i64_i32 v[10:11], s[4:5], v18, s12, v[120:121]
	v_lshl_add_u64 v[10:11], v[10:11], 0, v[122:123]
	global_store_dwordx2 v[10:11], v[8:9], off
	v_mul_f32_e32 v8, 0xbfb8aa3b, v0
	v_mul_f32_e32 v9, 0xbfb8aa3b, v1
	v_exp_f32_e32 v8, v8
	v_exp_f32_e32 v9, v9
	s_cselect_b64 s[4:5], -1, 0
	v_add_f32_e32 v8, 1.0, v8
	v_add_f32_e32 v9, 1.0, v9
	v_rcp_f32_e32 v8, v8
	v_rcp_f32_e32 v9, v9
	s_nop 0
	v_pk_mul_f32 v[0:1], v[0:1], v[8:9]
	s_nop 0
	v_pk_mul_f32 v[0:1], v[0:1], v[4:5]
	s_nop 0
	v_cvt_pk_f16_f32 v0, v0, v1
	v_mul_f32_e32 v1, 0xbfb8aa3b, v2
	v_exp_f32_e32 v1, v1
	s_nop 0
	v_add_f32_e32 v1, 1.0, v1
	v_rcp_f32_e32 v4, v1
	v_mul_f32_e32 v1, 0xbfb8aa3b, v3
	v_exp_f32_e32 v1, v1
	s_nop 0
	v_add_f32_e32 v1, 1.0, v1
	v_rcp_f32_e32 v5, v1
	s_nop 0
	v_pk_mul_f32 v[2:3], v[2:3], v[4:5]
	s_nop 0
	v_pk_mul_f32 v[2:3], v[2:3], v[6:7]
	s_nop 0
	v_cvt_pk_f16_f32 v1, v2, v3
	global_store_dwordx2 v[10:11], v[0:1], off offset:32
	s_waitcnt lgkmcnt(0)
	s_barrier

.LBB0_1761:
	s_ashr_i32 s5, s13, 31
	s_lshr_b32 s5, s5, 29
	s_add_i32 s5, s13, s5
	s_ashr_i32 s14, s5, 3
	s_and_b32 s5, s5, -8
	s_sub_i32 s5, s13, s5
	s_lshr_b32 s13, s5, 31
	s_or_b32 s13, s13, 0xb0
	s_mul_i32 s13, s13, s5
	s_add_i32 s13, s13, s14
	s_mul_hi_i32 s5, s13, 0x2e8ba2e9
	s_lshr_b32 s14, s5, 31
	s_ashr_i32 s25, s5, 5
	s_add_i32 s25, s25, s14
	s_lshl_b32 s5, s25, 3
	s_sub_i32 s14, 64, s5
	s_min_u32 s16, s14, 8
	s_mul_i32 s26, s25, 0xb0
	s_sub_i32 s17, s13, s26
	v_cvt_f32_ubyte0_e32 v1, s16
	v_cvt_f32_i32_e32 v0, s17
	v_rcp_iflag_f32_e32 v2, v1
	s_ashr_i32 s14, s17, 30
	v_mov_b32_e32 v136, v130
	s_or_b32 s24, s14, 1
	v_mul_f32_e32 v2, v0, v2
	v_trunc_f32_e32 v2, v2
	v_fma_f32 v0, -v2, v1, v0
	v_cmp_ge_f32_e64 s[14:15], |v0|, v1
	v_cvt_i32_f32_e32 v2, v2
	v_bfe_i32 v1, v136, 27, 1
	v_lshlrev_b32_e32 v141, 4, v136
	v_lshrrev_b32_e32 v1, 22, v1
	v_ashrrev_i32_e32 v0, 31, v136
	v_add_u32_e32 v1, v141, v1
	v_lshrrev_b32_e32 v0, 26, v0
	v_and_b32_e32 v1, 0xfffffc00, v1
	s_and_b64 s[14:15], s[14:15], exec
	v_add_u32_e32 v0, v136, v0
	v_sub_u32_e32 v1, v141, v1
	v_readfirstlane_b32 s15, v2
	v_ashrrev_i32_e32 v0, 6, v0
	v_lshrrev_b32_e32 v2, 4, v1
	v_bitop3_b32 v2, v2, v1, 32 bitop3:0x6c
	v_lshlrev_b32_e32 v1, 3, v0
	v_and_b32_e32 v3, 0x1ffff0, v1
	v_ashrrev_i32_e32 v1, 31, v2
	v_lshrrev_b32_e32 v1, 26, v1
	s_cselect_b32 s14, s24, 0
	v_add_u32_e32 v4, v2, v1
	s_add_i32 s27, s15, s14
	v_ashrrev_i32_e32 v1, 6, v4
	v_and_b32_e32 v4, 0xc0, v4
	s_sext_i32_i16 s24, s27
	s_mul_i32 s27, s27, s16
	v_sub_u32_e32 v2, v2, v4
	s_sub_i32 s14, s17, s27
	v_lshlrev_b32_e32 v5, 5, v0
	v_ashrrev_i16_sdwa v2, v225, sext(v2) dst_sel:DWORD dst_unused:UNUSED_PAD src0_sel:DWORD src1_sel:BYTE_0
	s_sext_i32_i16 s14, s14
	v_and_b32_e32 v5, 32, v5
	v_bfe_i32 v2, v2, 0, 16
	s_add_i32 s5, s5, s14
	v_add_u32_e32 v4, v5, v2
	v_add_lshl_u32 v3, v1, v3, 11
	v_add_u32_e32 v135, 16, v141
	s_lshl_b32 s14, s5, 8
	s_lshl_b32 s16, s24, 8
	v_lshl_add_u32 v194, v4, 1, v3
	s_andn2_b64 vcc, exec, s[18:19]
	v_add_u32_e32 v134, 0x2000, v135
	v_add_u32_e32 v133, s75, v141
	v_add_u32_e32 v132, 0x4000, v135
	v_add_u32_e32 v131, 0x6000, v135
	s_mov_b32 s100, 1
	s_cbranch_vccnz .LBB0_1763
	s_mov_b32 s100, 0
	s_ashr_i32 s17, s16, 31
	s_lshl_b64 s[18:19], s[16:17], 11
	s_add_u32 s18, s20, s18
	s_addc_u32 s19, s21, s19
	s_add_i32 s5, 16, 0x10000
	v_add_u32_e32 v3, s5, v141
	s_ashr_i32 s15, s14, 31
	v_readfirstlane_b32 s5, v3
	s_mov_b32 m0, s5
	v_add_u32_e32 v3, 0x2000, v3
	v_lshl_add_u64 v[4:5], s[18:19], 0, v[194:195]
	global_load_lds_dwordx4 v194, s[18:19]
	s_mov_b64 s[34:35], 0x20000
	v_readfirstlane_b32 s5, v3
	s_lshl_b64 s[18:19], s[14:15], 11
	v_lshl_add_u64 v[4:5], v[4:5], 0, s[34:35]
	s_mov_b32 m0, s5
	s_add_u32 s18, s96, s18
	v_readfirstlane_b32 s5, v135
	global_load_lds_dwordx4 v[4:5], off
	s_addc_u32 s19, s97, s19
	s_mov_b32 m0, s5
	v_lshl_add_u64 v[4:5], s[18:19], 0, v[194:195]
	global_load_lds_dwordx4 v194, s[18:19]
	s_or_b32 s18, s16, 0x80
	s_ashr_i32 s19, s18, 31
	v_readfirstlane_b32 s5, v134
	s_lshl_b64 s[18:19], s[18:19], 11
	v_lshl_add_u64 v[4:5], v[4:5], 0, s[34:35]
	s_mov_b32 m0, s5
	s_add_u32 s18, s20, s18
	v_readfirstlane_b32 s5, v133
	global_load_lds_dwordx4 v[4:5], off
	s_addc_u32 s19, s21, s19
	s_mov_b32 m0, s5
	v_lshl_add_u64 v[4:5], s[18:19], 0, v[194:195]
	global_load_lds_dwordx4 v194, s[18:19]
	s_or_b32 s18, s14, 0x80
	s_ashr_i32 s19, s18, 31
	v_add_u32_e32 v3, 0x2000, v133
	s_lshl_b64 s[18:19], s[18:19], 11
	v_readfirstlane_b32 s5, v3
	s_add_u32 s18, s96, s18
	v_lshl_add_u64 v[4:5], v[4:5], 0, s[34:35]
	s_mov_b32 m0, s5
	s_addc_u32 s19, s97, s19
	v_readfirstlane_b32 s5, v132
	global_load_lds_dwordx4 v[4:5], off
	v_lshl_add_u64 v[4:5], s[18:19], 0, v[194:195]
	s_mov_b32 m0, s5
	v_readfirstlane_b32 s5, v131
	global_load_lds_dwordx4 v194, s[18:19]
	v_lshl_add_u64 v[4:5], v[4:5], 0, s[34:35]
	s_mov_b32 m0, s5
	s_nop 0
	global_load_lds_dwordx4 v[4:5], off

.LBB0_1765:
	s_or_b64 exec, exec, s[18:19]
	s_ashr_i32 s17, s16, 31
	v_and_b32_e32 v140, 15, v136
	s_lshl_b64 s[18:19], s[16:17], 11
	v_bfe_u32 v139, v136, 4, 2
	v_lshlrev_b32_e32 v3, 6, v140
	v_lshlrev_b32_e32 v4, 2, v136
	s_add_u32 s34, s20, s18
	v_bfe_u32 v138, v136, 6, 2
	v_lshl_or_b32 v3, v139, 4, v3
	v_and_b32_e32 v4, 32, v4
	v_lshlrev_b32_e32 v5, 13, v137
	s_addc_u32 s35, s21, s19
	s_add_i32 s5, 16, 0x18000
	v_bitop3_b32 v8, v3, v5, v4 bitop3:0xde
	v_lshlrev_b32_e32 v5, 12, v138
	v_add_u32_e32 v144, s5, v141
	v_bitop3_b32 v143, v3, v5, v4 bitop3:0xde
	v_lshl_add_u64 v[4:5], s[34:35], 0, v[194:195]
	s_mov_b64 s[36:37], 0x80
	v_readfirstlane_b32 s15, v144
	v_add_u32_e32 v145, 0x2000, v144
	v_lshl_add_u64 v[6:7], v[4:5], 0, s[36:37]
	s_mov_b32 m0, s15
	v_readfirstlane_b32 s15, v145
	s_cmp_eq_u32 s100, 0
	s_cbranch_scc1 .Lnw8a_a
	s_waitcnt vmcnt(20)
	s_branch .Lnw8a_b

.Lnw8a_b:
	s_barrier
	global_load_lds_dwordx4 v[6:7], off
	s_mov_b32 m0, s15
	s_ashr_i32 s15, s14, 31
	s_lshl_b64 s[34:35], s[14:15], 11
	s_add_u32 s34, s96, s34
	s_mov_b64 s[38:39], 0x20080
	s_addc_u32 s35, s97, s35
	s_bitset1_b32 s16, 7
	v_lshl_add_u64 v[4:5], v[4:5], 0, s[38:39]
	v_add_u32_e32 v146, 0x8000, v135
	s_ashr_i32 s17, s16, 31
	global_load_lds_dwordx4 v[4:5], off
	v_lshl_add_u64 v[4:5], s[34:35], 0, v[194:195]
	v_readfirstlane_b32 s15, v146
	v_add_u32_e32 v147, 0xa000, v135
	s_lshl_b64 s[16:17], s[16:17], 11
	v_lshl_add_u64 v[6:7], v[4:5], 0, s[36:37]
	s_mov_b32 m0, s15
	v_readfirstlane_b32 s15, v147
	s_add_u32 s16, s20, s16
	global_load_lds_dwordx4 v[6:7], off
	v_lshl_add_u64 v[4:5], v[4:5], 0, s[38:39]
	s_mov_b32 m0, s15
	s_addc_u32 s17, s21, s17
	v_add_u32_e32 v148, s2, v141
	global_load_lds_dwordx4 v[4:5], off
	v_lshl_add_u64 v[4:5], s[16:17], 0, v[194:195]
	v_readfirstlane_b32 s15, v148
	v_add_u32_e32 v149, 0x2000, v148
	v_lshl_add_u64 v[6:7], v[4:5], 0, s[36:37]
	s_mov_b32 m0, s15
	v_readfirstlane_b32 s15, v149
	global_load_lds_dwordx4 v[6:7], off
	v_lshl_add_u64 v[4:5], v[4:5], 0, s[38:39]
	s_mov_b32 m0, s15
	s_add_u32 s16, s30, s18
	global_load_lds_dwordx4 v[4:5], off
	s_addc_u32 s17, s31, s19
	s_sub_i32 s13, s13, s27
	s_sub_i32 s13, s13, s26
	s_sext_i32_i16 s13, s13
	v_lshlrev_b32_e32 v3, 14, v0
	s_lshl_b32 s15, s25, 11
	s_lshl_b32 s13, s13, 8
	v_and_b32_e32 v3, 0xffff8000, v3
	s_add_i32 s18, s15, s13
	v_lshl_add_u32 v1, v1, 11, v3
	v_and_b32_e32 v0, 1, v0
	s_ashr_i32 s19, s18, 31
	s_cmp_eq_u32 s100, 0
	s_cbranch_scc1 .Lnw8b_a
	s_waitcnt vmcnt(22)
	s_branch .Lnw8b_b

.Lnw8b_b:
	v_lshl_or_b32 v0, v0, 6, v1
	s_lshl_b64 s[18:19], s[18:19], 11
	v_lshl_add_u32 v128, v2, 1, v0
	s_add_u32 s18, s46, s18
	v_mov_b32_e32 v0, 0
	v_mov_b32_e32 v129, v195
	s_addc_u32 s19, s47, s19
	s_mov_b32 s13, -2
	v_add_u32_e32 v142, 16, v8
	v_mov_b32_e32 v1, v0
	v_mov_b32_e32 v2, v0
	v_mov_b32_e32 v3, v0
	v_mov_b32_e32 v4, v0
	v_mov_b32_e32 v5, v0
	v_mov_b32_e32 v6, v0
	v_mov_b32_e32 v7, v0
	v_mov_b32_e32 v8, v0
	v_mov_b32_e32 v9, v0
	v_mov_b32_e32 v10, v0
	v_mov_b32_e32 v11, v0
	v_mov_b32_e32 v12, v0
	v_mov_b32_e32 v13, v0
	v_mov_b32_e32 v14, v0
	v_mov_b32_e32 v15, v0
	v_mov_b32_e32 v16, v0
	v_mov_b32_e32 v17, v0
	v_mov_b32_e32 v18, v0
	v_mov_b32_e32 v19, v0
	v_mov_b32_e32 v20, v0
	v_mov_b32_e32 v21, v0
	v_mov_b32_e32 v22, v0
	v_mov_b32_e32 v23, v0
	v_mov_b32_e32 v24, v0
	v_mov_b32_e32 v25, v0
	v_mov_b32_e32 v26, v0
	v_mov_b32_e32 v27, v0
	v_mov_b32_e32 v28, v0
	v_mov_b32_e32 v29, v0
	v_mov_b32_e32 v30, v0
	v_mov_b32_e32 v31, v0
	v_mov_b32_e32 v32, v0
	v_mov_b32_e32 v33, v0
	v_mov_b32_e32 v34, v0
	v_mov_b32_e32 v35, v0
	v_mov_b32_e32 v36, v0
	v_mov_b32_e32 v37, v0
	v_mov_b32_e32 v38, v0
	v_mov_b32_e32 v39, v0
	v_mov_b32_e32 v40, v0
	v_mov_b32_e32 v41, v0
	v_mov_b32_e32 v42, v0
	v_mov_b32_e32 v43, v0
	v_mov_b32_e32 v44, v0
	v_mov_b32_e32 v45, v0
	v_mov_b32_e32 v46, v0
	v_mov_b32_e32 v47, v0
	v_mov_b32_e32 v48, v0
	v_mov_b32_e32 v49, v0
	v_mov_b32_e32 v50, v0
	v_mov_b32_e32 v51, v0
	v_mov_b32_e32 v52, v0
	v_mov_b32_e32 v53, v0
	v_mov_b32_e32 v54, v0
	v_mov_b32_e32 v55, v0
	v_mov_b32_e32 v56, v0
	v_mov_b32_e32 v57, v0
	v_mov_b32_e32 v58, v0
	v_mov_b32_e32 v59, v0
	v_mov_b32_e32 v60, v0
	v_mov_b32_e32 v61, v0
	v_mov_b32_e32 v62, v0
	v_mov_b32_e32 v63, v0
	v_mov_b32_e32 v64, v0
	v_mov_b32_e32 v65, v0
	v_mov_b32_e32 v66, v0
	v_mov_b32_e32 v67, v0
	v_mov_b32_e32 v68, v0
	v_mov_b32_e32 v69, v0
	v_mov_b32_e32 v70, v0
	v_mov_b32_e32 v71, v0
	v_mov_b32_e32 v72, v0
	v_mov_b32_e32 v73, v0
	v_mov_b32_e32 v74, v0
	v_mov_b32_e32 v75, v0
	v_mov_b32_e32 v76, v0
	v_mov_b32_e32 v77, v0
	v_mov_b32_e32 v78, v0
	v_mov_b32_e32 v79, v0
	v_mov_b32_e32 v80, v0
	v_mov_b32_e32 v81, v0
	v_mov_b32_e32 v82, v0
	v_mov_b32_e32 v83, v0
	v_mov_b32_e32 v84, v0
	v_mov_b32_e32 v85, v0
	v_mov_b32_e32 v86, v0
	v_mov_b32_e32 v87, v0
	v_mov_b32_e32 v88, v0
	v_mov_b32_e32 v89, v0
	v_mov_b32_e32 v90, v0
	v_mov_b32_e32 v91, v0
	v_mov_b32_e32 v92, v0
	v_mov_b32_e32 v93, v0
	v_mov_b32_e32 v94, v0
	v_mov_b32_e32 v95, v0
	v_mov_b32_e32 v96, v0
	v_mov_b32_e32 v97, v0
	v_mov_b32_e32 v98, v0
	v_mov_b32_e32 v99, v0
	v_mov_b32_e32 v100, v0
	v_mov_b32_e32 v101, v0
	v_mov_b32_e32 v102, v0
	v_mov_b32_e32 v103, v0
	v_mov_b32_e32 v104, v0
	v_mov_b32_e32 v105, v0
	v_mov_b32_e32 v106, v0
	v_mov_b32_e32 v107, v0
	v_mov_b32_e32 v108, v0
	v_mov_b32_e32 v109, v0
	v_mov_b32_e32 v110, v0
	v_mov_b32_e32 v111, v0
	v_mov_b32_e32 v112, v0
	v_mov_b32_e32 v113, v0
	v_mov_b32_e32 v114, v0
	v_mov_b32_e32 v115, v0
	v_mov_b32_e32 v116, v0
	v_mov_b32_e32 v117, v0
	v_mov_b32_e32 v118, v0
	v_mov_b32_e32 v119, v0
	v_mov_b32_e32 v120, v0
	v_mov_b32_e32 v121, v0
	v_mov_b32_e32 v122, v0
	v_mov_b32_e32 v123, v0
	v_mov_b32_e32 v124, v0
	v_mov_b32_e32 v125, v0
	v_mov_b32_e32 v126, v0
	v_mov_b32_e32 v127, v0
	s_mov_b64 s[26:27], 0x3240080
	s_mov_b64 s[34:35], 0x3260080
	s_mov_b64 s[36:37], 0x3200100
	s_mov_b64 s[38:39], 0x3220100
	s_mov_b64 s[40:41], 0x3240100
	s_mov_b64 s[42:43], 0x3260100
	s_mov_b64 s[44:45], 0x3200180
	s_mov_b64 s[86:87], 0x3220180
	s_mov_b64 s[10:11], 0x1e80100
	s_mov_b64 s[56:57], 0x1ea0100
	s_mov_b64 s[58:59], 0x1ec0100
	s_mov_b64 s[60:61], 0x1ee0100
	s_mov_b64 s[76:77], 0x1e80180
	s_mov_b64 s[82:83], 0x1ea0180
	s_mov_b64 s[94:95], 0x1ec0180
	s_mov_b64 vcc, 0x1ee0180
	s_barrier

	.amdhsa_kernel _Z10fwd_kernel6Params
		.amdhsa_group_segment_fixed_size 16
		.amdhsa_private_segment_fixed_size 0
		.amdhsa_kernarg_size 496
		.amdhsa_user_sgpr_count 2
		.amdhsa_user_sgpr_dispatch_ptr 0
		.amdhsa_user_sgpr_queue_ptr 0
		.amdhsa_user_sgpr_kernarg_segment_ptr 1
		.amdhsa_user_sgpr_dispatch_id 0
		.amdhsa_user_sgpr_kernarg_preload_length 0
		.amdhsa_user_sgpr_kernarg_preload_offset 0
		.amdhsa_user_sgpr_private_segment_size 0
		.amdhsa_uses_dynamic_stack 0
		.amdhsa_enable_private_segment 0
		.amdhsa_system_sgpr_workgroup_id_x 1
		.amdhsa_system_sgpr_workgroup_id_y 0
		.amdhsa_system_sgpr_workgroup_id_z 0
		.amdhsa_system_sgpr_workgroup_info 0
		.amdhsa_system_vgpr_workitem_id 2
		.amdhsa_next_free_vgpr 256
		.amdhsa_next_free_sgpr 102
		.amdhsa_accum_offset 256
		.amdhsa_reserve_vcc 1
		.amdhsa_float_round_mode_32 0
		.amdhsa_float_round_mode_16_64 0
		.amdhsa_float_denorm_mode_32 3
		.amdhsa_float_denorm_mode_16_64 3
		.amdhsa_dx10_clamp 1
		.amdhsa_ieee_mode 1
		.amdhsa_fp16_overflow 0
		.amdhsa_tg_split 0
		.amdhsa_exception_fp_ieee_invalid_op 0
		.amdhsa_exception_fp_denorm_src 0
		.amdhsa_exception_fp_ieee_div_zero 0
		.amdhsa_exception_fp_ieee_overflow 0
		.amdhsa_exception_fp_ieee_underflow 0
		.amdhsa_exception_fp_ieee_inexact 0
		.amdhsa_exception_int_div_zero 0
	.end_amdhsa_kernel

amdhsa.kernels:
  - .agpr_count:     0
    .args:
      - .offset:         0
        .size:           240
        .value_kind:     by_value
      - .offset:         240
        .size:           4
        .value_kind:     hidden_block_count_x
      - .offset:         244
        .size:           4
        .value_kind:     hidden_block_count_y
      - .offset:         248
        .size:           4
        .value_kind:     hidden_block_count_z
      - .offset:         252
        .size:           2
        .value_kind:     hidden_group_size_x
      - .offset:         254
        .size:           2
        .value_kind:     hidden_group_size_y
      - .offset:         256
        .size:           2
        .value_kind:     hidden_group_size_z
      - .offset:         258
        .size:           2
        .value_kind:     hidden_remainder_x
      - .offset:         260
        .size:           2
        .value_kind:     hidden_remainder_y
      - .offset:         262
        .size:           2
        .value_kind:     hidden_remainder_z
      - .offset:         280
        .size:           8
        .value_kind:     hidden_global_offset_x
      - .offset:         288
        .size:           8
        .value_kind:     hidden_global_offset_y
      - .offset:         296
        .size:           8
        .value_kind:     hidden_global_offset_z
      - .offset:         304
        .size:           2
        .value_kind:     hidden_grid_dims
      - .offset:         328
        .size:           8
        .value_kind:     hidden_multigrid_sync_arg
      - .offset:         360
        .size:           4
        .value_kind:     hidden_dynamic_lds_size
    .group_segment_fixed_size: 16
    .kernarg_segment_align: 8
    .kernarg_segment_size: 496
    .language:       OpenCL C
    .language_version:
      - 2
      - 0
    .max_flat_workgroup_size: 512
    .name:           _Z10fwd_kernel6Params
    .private_segment_fixed_size: 0
    .sgpr_count:     108
    .sgpr_spill_count: 266
    .symbol:         _Z10fwd_kernel6Params.kd
    .uniform_work_group_size: 1
    .uses_dynamic_stack: false
    .vgpr_count:     256
    .vgpr_spill_count: 0
    .wavefront_size: 64
